# P0: row-norm loop workgroup index rotated by 64 so the workgroups with a ninth transposition tile take four rows instead of five
# baseline (speedup 1.0000x reference)
; DEV void store_bf4(bf16_t* p, f32x4 v) { uint2 w; w.x = cvt_pk_bf16(v[0], v[1]); w.y = cvt_pk_bf16(v[2], v[3]); *(uint2*)p = w; }
; DEV void rmsnorm_row_bf16(const float* __restrict__ x, const float* __restrict__ g, bf16_t* __restrict__ y, int lane) {
;     f32x4 v[8]; float ss = 0.f;
; #pragma unroll
;     for (int i = 0; i < 8; ++i) { v[i] = __builtin_nontemporal_load((const f32x4*)x + i * 64 + lane); ss += v[i][0] * v[i][0] + v[i][1] * v[i][1] + v[i][2] * v[i][2] + v[i][3] * v[i][3]; }
;     ss = wave_sum(ss);
;     const float rs = rsqrtf(ss * (1.f / 2048.f) + EPS);
; #pragma unroll
;     for (int i = 0; i < 8; ++i) { const f32x4 gg = ((const f32x4*)g)[i * 64 + lane]; store_bf4(y + (size_t)(i * 64 + lane) * 4, v[i] * rs * gg); }
; __global__ void __launch_bounds__(512) hymba_fwd(Params p) {
;     ...
;         for (int r = bid * 8 + wid; r < TT + 1024; r += G * 8) {
;             if (r < TP) rmsnorm_row_bf16(p.in[0] + (size_t)r * D, p.in[8], hbuf + (size_t)r * LDB, lane);
;             else if (r < TT) rmsnorm_row_bf16(p.in[1] + (size_t)(r - TP) * D, p.in[8], hbuf + (size_t)r * LDB, lane);
;             else rmsnorm_row_bf16(p.in[2] + (size_t)(r - TT) * D, p.in[17], hm + (size_t)(r - TT) * LDB, lane);
.LBB0_106:
	s_mov_b32 s96, s2
	s_cmpk_lg_i32 s33, 0x100
	s_cbranch_scc1 .Lp0n_done
	s_sub_i32 s96, s2, 64
	s_and_b32 s96, s96, 0xff
.Lp0n_done:
	v_ashrrev_i32_e32 v2, 6, v1
	v_lshl_add_u32 v34, s96, 3, v2
	s_movk_i32 s4, 0x2600
	v_cmp_gt_i32_e32 vcc, s4, v34
	s_and_saveexec_b64 s[8:9], vcc
	s_cbranch_execz .LBB0_117
	s_load_dwordx4 s[4:7], s[0:1], 0x0
	s_load_dwordx2 s[10:11], s[0:1], 0x10
	v_and_b32_e32 v1, 63, v1
	s_load_dwordx2 s[12:13], s[0:1], 0x88
	v_or_b32_e32 v3, 0x100, v1
	v_lshlrev_b32_e32 v4, 4, v3
	v_lshlrev_b32_e32 v52, 3, v3
	v_or_b32_e32 v3, 0x140, v1
	v_lshlrev_b32_e32 v36, 4, v1
	v_mov_b32_e32 v37, 0
	v_lshlrev_b32_e32 v42, 3, v1
	v_lshlrev_b32_e32 v6, 4, v3
	v_lshlrev_b32_e32 v56, 3, v3
	v_or_b32_e32 v3, 0x180, v1
	v_or_b32_e32 v1, 0x1c0, v1
	v_mov_b32_e32 v43, v37
	v_mov_b32_e32 v5, v37
	v_mov_b32_e32 v7, v37
	v_lshlrev_b32_e32 v8, 4, v3
	v_mov_b32_e32 v9, v37
	v_lshlrev_b32_e32 v10, 4, v1
	v_mov_b32_e32 v11, v37
	s_movk_i32 s22, 0x1080
	s_waitcnt lgkmcnt(0)
	v_lshl_add_u64 v[38:39], s[10:11], 0, v[36:37]
	s_load_dwordx2 s[10:11], s[0:1], 0x40
	v_lshl_add_u64 v[40:41], s[12:13], 0, v[36:37]
	v_lshl_add_u64 v[50:51], s[12:13], 0, v[4:5]
	v_lshl_add_u64 v[54:55], s[12:13], 0, v[6:7]
	v_lshl_add_u64 v[58:59], s[12:13], 0, v[8:9]
	v_lshlrev_b32_e32 v60, 3, v3
	v_lshl_add_u64 v[62:63], s[12:13], 0, v[10:11]
	v_lshlrev_b32_e32 v64, 3, v1
	v_mul_lo_u32 v1, v2, s22
	v_mad_i64_i32 v[2:3], s[12:13], v34, s22, v[42:43]
	v_ashrrev_i32_e32 v35, 31, v34
	v_lshl_add_u64 v[2:3], v[158:159], 0, v[2:3]
	s_mov_b64 s[12:13], 0x4318000
	v_lshl_add_u64 v[80:81], v[2:3], 0, s[12:13]
	v_lshlrev_b64 v[2:3], 13, v[34:35]
	v_or_b32_e32 v2, v2, v36
	v_lshl_add_u64 v[2:3], s[4:5], 0, v[2:3]
	s_mov_b64 s[4:5], 0x1000
	v_lshl_add_u64 v[82:83], v[2:3], 0, s[4:5]
	v_mbcnt_lo_u32_b32 v2, -1, 0
	v_lshl_add_u64 v[66:67], s[6:7], 0, v[36:37]
	s_lshl_b32 s6, s33, 3
	s_mul_i32 s7, s96, 0x8400
	v_mbcnt_hi_u32_b32 v35, -1, v2
	v_add_u32_e32 v78, s7, v1
	s_ashr_i32 s7, s6, 31
	v_and_b32_e32 v2, 64, v35
	v_or_b32_e32 v44, 0x200, v42
	v_mov_b32_e32 v45, v37
	v_or_b32_e32 v46, 0x400, v42
	v_mov_b32_e32 v47, v37
	v_or_b32_e32 v48, 0x600, v42
	v_mov_b32_e32 v49, v37
	v_mov_b32_e32 v53, v37
	v_mov_b32_e32 v57, v37
	v_mov_b32_e32 v61, v37
	v_mov_b32_e32 v65, v37
	s_waitcnt lgkmcnt(0)
	v_lshl_add_u64 v[68:69], s[10:11], 0, v[36:37]
	v_lshl_add_u64 v[70:71], s[10:11], 0, v[4:5]
	v_lshl_add_u64 v[72:73], s[10:11], 0, v[6:7]
	v_lshl_add_u64 v[74:75], s[10:11], 0, v[8:9]
	v_lshl_add_u64 v[76:77], s[10:11], 0, v[10:11]
	s_mul_i32 s10, s33, 0x8400
	s_mul_hi_i32 s11, s6, 0x1080
	s_lshl_b64 s[4:5], s[6:7], 13
	s_mov_b64 s[12:13], 0
	s_movk_i32 s7, 0x1fff
	s_mov_b64 s[16:17], 0xe00
	s_movk_i32 s23, 0x21ff
	s_movk_i32 s24, 0x1000
	v_mov_b32_e32 v1, 0x358637bd
	s_mov_b32 s25, 0x800000
	s_movk_i32 s26, 0x25ff
	v_add_u32_e32 v86, 64, v2
	v_xor_b32_e32 v87, 32, v35
	v_xor_b32_e32 v88, 16, v35
	v_xor_b32_e32 v89, 8, v35
	v_xor_b32_e32 v90, 4, v35
	v_xor_b32_e32 v91, 2, v35
	v_xor_b32_e32 v92, 1, v35
	s_branch .LBB0_109
